# post1 row loop: B q/k row data prefetched with the first section's loads, remaining rotary and norm tables cached in registers (two more dependent round trips removed per row)
# speedup vs baseline: 1.0045x; 1.0045x over previous
; #define TIDX ((int)((wave_s << 6) | lane_id_v()))
; __device__ __forceinline__ void phase_post1(const Params& p, int layer, const int wave_s) {
;   int t_ = TIDX; asm volatile("" : "+v"(t_)); const int lane = t_ & 63, wave = __builtin_amdgcn_readfirstlane(t_ >> 6), gw = blockIdx.x * 8 + wave, NGW = gridDim.x * 8; (void)wave;
;   bf16_t* P = (bf16_t*)(p.ws + WS_P); bf16_t* POOL = (bf16_t*)(p.ws + WS_POOL); bf16_t* KC = (bf16_t*)(p.ws + WS_KC);
;   const float* aqn = p.a_q_norm + layer * 64; const float* akn = p.a_k_norm + layer * 64;
;   const float* bqn = p.b_q_norm + layer * 128; const float* bkn = p.b_k_norm + layer * 128;
;   const float* cql = p.c_q_lat + layer * 384; const float* ckvl = p.c_kv_lat + layer * 256; const float* ckn = p.c_k_norm + layer * 192;
;   for (int r = gw; r < MP; r += NGW) {
;     if (r >= LROWS) {
;       *(u32x4*)(POOL + (size_t)r * 512 + lane * 8) = (u32x4){0u, 0u, 0u, 0u};
;       for (int i = lane; i < 768 / 8; i += 64) *(u32x4*)(KC + (size_t)r * 768 + i * 8) = (u32x4){0u, 0u, 0u, 0u};
;       continue; }
;     bf16_t* pr = P + (size_t)r * INP;
;     const float posf = (float)r;
;     const float rowp = (r < NMETA) ? -1.f : (float)((r - NMETA) >> 6), colp = (r < NMETA) ? (float)r : (float)((r - NMETA) & 63);
.LBB0_201:
	s_or_b64 exec, exec, s[0:1]
	s_waitcnt lgkmcnt(0)
	s_barrier
	v_mbcnt_lo_u32_b32 v0, -1, 0
	v_mbcnt_hi_u32_b32 v0, -1, v0
	s_mul_i32 s22, s70, 0xc0
	v_or_b32_e32 v0, s61, v0
	s_nop 0
	v_readfirstlane_b32 s0, v0
	s_ashr_i32 s0, s0, 6
	s_add_i32 s4, s0, s75
	s_cmpk_gt_i32 s4, 0x40ff
	s_cbranch_scc1 .LBB0_216
	s_mul_i32 s0, s70, 0x180
	s_mov_b32 s1, s5
	v_readlane_b32 s40, v254, 27
	s_lshl_b64 s[0:1], s[0:1], 2
	v_readlane_b32 s52, v254, 39
	v_readlane_b32 s53, v254, 40
	s_add_u32 s0, s52, s0
	s_mov_b32 s23, s5
	v_readlane_b32 s24, v254, 15
	s_addc_u32 s1, s53, s1
	s_lshl_b32 s2, s70, 7
	s_lshl_b64 s[6:7], s[22:23], 2
	v_readlane_b32 s26, v254, 17
	v_and_b32_e32 v64, 63, v0
	v_readlane_b32 s27, v254, 18
	s_add_u32 s6, s26, s6
	v_readlane_b32 s41, v254, 28
	v_readlane_b32 s43, v254, 30
	s_addc_u32 s7, s27, s7
	s_lshl_b32 s8, s70, 8
	s_mov_b32 s9, s5
	v_cmp_gt_u32_e64 s[36:37], 32, v64
	v_mov_b32_e32 v1, 0x3e38aa3b
	v_readlane_b32 s42, v254, 29
	v_readlane_b32 s54, v254, 41
	s_lshl_b64 s[8:9], s[8:9], 2
	v_cndmask_b32_e64 v65, 1.0, v1, s[36:37]
	v_mov_b32_e32 v1, s43
	v_mov_b32_e32 v2, s41
	v_readlane_b32 s55, v254, 42
	s_add_u32 s8, s54, s8
	v_cndmask_b32_e64 v3, v1, v2, s[36:37]
	v_mov_b32_e32 v1, s42
	v_mov_b32_e32 v2, s40
	s_addc_u32 s9, s55, s9
	s_lshl_b32 s18, s70, 6
	s_mov_b32 s19, s5
	v_cndmask_b32_e64 v2, v1, v2, s[36:37]
	v_and_b32_e32 v1, 3, v0
	v_lshl_add_u64 v[2:3], s[18:19], 2, v[2:3]
	v_lshlrev_b32_e32 v4, 6, v1
	v_mov_b32_e32 v5, v169
	v_lshl_add_u64 v[66:67], v[2:3], 0, v[4:5]
	v_and_b32_e32 v2, 4, v0
	v_lshlrev_b32_e32 v168, 4, v64
	v_cmp_eq_u32_e64 s[42:43], 0, v2
	v_lshlrev_b32_e32 v2, 2, v64
	v_mov_b32_e32 v3, v169
	s_mov_b32 s3, s5
	v_lshl_add_u64 v[70:71], s[8:9], 0, v[168:169]
	v_lshl_add_u64 v[72:73], s[6:7], 0, v[2:3]
	v_and_b32_e32 v2, 31, v0
	v_readlane_b32 s8, v251, 0
	v_readlane_b32 s6, v252, 16
	v_readlane_b32 s48, v254, 35
	v_lshlrev_b32_e32 v2, 2, v2
	v_readlane_b32 s9, v251, 1
	v_readlane_b32 s7, v252, 17
	s_lshl_b64 s[2:3], s[2:3], 2
	v_readlane_b32 s44, v254, 31
	v_readlane_b32 s45, v254, 32
	v_readlane_b32 s49, v254, 36
	v_lshl_add_u64 v[74:75], s[8:9], 0, v[2:3]
	v_and_b32_e32 v2, 32, v0
	v_lshl_add_u64 v[76:77], s[6:7], 0, v[168:169]
	s_add_u32 s6, s48, s2
	v_readlane_b32 s50, v254, 37
	v_cmp_eq_u32_e64 s[38:39], 0, v1
	v_and_b32_e32 v1, 15, v0
	v_cmp_eq_u32_e64 s[44:45], 0, v2
	v_bfe_u32 v2, v0, 4, 2
	s_addc_u32 s7, s49, s3
	v_lshlrev_b32_e32 v0, 5, v0
	v_readlane_b32 s51, v254, 38
	v_cmp_gt_u32_e64 s[40:41], 8, v1
	v_lshlrev_b32_e64 v102, v2, 1
	v_lshlrev_b32_e32 v2, 5, v1
	v_and_b32_e32 v0, 0x60, v0
	v_mov_b32_e32 v1, v169
	s_add_u32 s2, s50, s2
	v_lshl_add_u64 v[80:81], s[8:9], 0, v[0:1]
	s_addc_u32 s3, s51, s3
	v_or_b32_e32 v0, 64, v64
	v_lshl_add_u64 v[78:79], s[6:7], 0, v[2:3]
	v_lshl_add_u64 v[82:83], s[2:3], 0, v[2:3]
	v_or_b32_e32 v2, 0x80, v64
	v_lshlrev_b32_e32 v6, 3, v0
	v_mov_b32_e32 v7, v169
	v_lshlrev_b32_e32 v68, 3, v64
	v_mov_b32_e32 v69, v169
	v_lshl_add_u64 v[86:87], s[0:1], 0, v[6:7]
	v_lshlrev_b32_e32 v6, 3, v2
	v_lshl_add_u64 v[84:85], s[0:1], 0, v[68:69]
	v_lshl_add_u64 v[88:89], s[0:1], 0, v[6:7]
	v_readlane_b32 s0, v252, 14
	v_lshlrev_b32_e32 v4, 1, v64
	v_readlane_b32 s1, v252, 15
	v_lshl_add_u64 v[92:93], s[10:11], 0, v[168:169]
	v_or_b32_e32 v69, 0xffffffc0, v64
	v_lshl_add_u64 v[90:91], s[0:1], 0, v[4:5]
	v_lshl_add_u64 v[94:95], s[0:1], 0, v[168:169]
	v_lshlrev_b32_e32 v100, 1, v168
	v_lshlrev_b32_e32 v103, 2, v0
	v_lshlrev_b32_e32 v104, 2, v2
	s_movk_i32 s18, 0x2000
	v_readlane_b32 s46, v254, 33
	v_readlane_b32 s47, v254, 34
	v_readlane_b32 s25, v254, 16
	global_load_dwordx4 v[114:117], v[80:81], off offset:216
	global_load_dwordx4 v[118:121], v[80:81], off offset:200
	global_load_dwordx4 v[122:125], v[78:79], off offset:16
	global_load_dwordx4 v[126:129], v[78:79], off
	global_load_dwordx4 v[142:145], v[82:83], off
	global_load_dwordx4 v[146:149], v[82:83], off offset:16
	v_lshlrev_b32_e32 v130, 1, v68
	v_add_u32_e32 v130, 16, v130
	v_add_u32_e32 v131, 0x400, v130
	s_waitcnt vmcnt(0)
	s_branch .LBB0_204

; __device__ __forceinline__ void unpack8(const u32x4 w, float* x) { x[0] = bflo(w.x); x[1] = bfhi(w.x); x[2] = bflo(w.y); x[3] = bfhi(w.y); x[4] = bflo(w.z); x[5] = bfhi(w.z); x[6] = bflo(w.w); x[7] = bfhi(w.w); }
; __device__ __forceinline__ void phase_post1(const Params& p, int layer, const int wave_s) {
;     ...
;     const float posf = (float)r;
;     const float rowp = (r < NMETA) ? -1.f : (float)((r - NMETA) >> 6), colp = (r < NMETA) ? (float)r : (float)((r - NMETA) & 63);
;     { float x[16]; u32x4* ptr = (u32x4*)(pr + C_AQ + lane * 16); const u32x4 w0 = ptr[0], w1 = ptr[1]; unpack8(w0, x); unpack8(w1, x + 8);
;       float ss = 0.f;
; #pragma unroll
;       for (int i = 0; i < 16; ++i) ss += x[i] * x[i];
;       ss += __shfl_xor(ss, 1); ss += __shfl_xor(ss, 2);
;       const float rs = rsqrtf(ss * (1.f / 64.f) + EPS) * ((lane >> 5) ? 1.f : QS_A);
;       const float* wn = ((lane >> 5) ? akn : aqn) + (lane & 3) * 16;
; #pragma unroll
;       for (int i = 0; i < 16; ++i) x[i] = x[i] * rs * wn[i];
;       if ((lane & 3) == 0) {
.LBB0_204:
	s_cmpk_lt_i32 s4, 0x4010
	s_mov_b64 s[0:1], -1
	s_cbranch_scc0 .LBB0_212
	s_mul_i32 s1, s4, 0x2e00
	s_mul_hi_i32 s0, s4, 0x2e00
	s_add_u32 s34, s10, s1
	s_addc_u32 s35, s11, s0
	global_load_dwordx4 v[0:3], v100, s[34:35]
	global_load_dwordx4 v[4:7], v100, s[34:35] offset:16
	global_load_dwordx4 v[8:11], v[66:67], off
	global_load_dwordx4 v[20:23], v[66:67], off offset:16
	global_load_dwordx4 v[24:27], v[66:67], off offset:32
	global_load_dwordx4 v[28:31], v[66:67], off offset:48
	global_load_dwordx4 v[134:137], v130, s[34:35] offset:4080
	global_load_dwordx4 v[138:141], v131, s[34:35] offset:4080
	v_cmp_lt_i32_e32 vcc, v198, v197
	v_cvt_f32_i32_e32 v38, s4
	v_mov_b32_e32 v101, v169
	v_cndmask_b32_e32 v12, v196, v198, vcc
	v_lshlrev_b32_e32 v39, 2, v12
	v_cmp_lt_i32_e32 vcc, v199, v197
	s_waitcnt vmcnt(7)
	v_lshlrev_b32_e32 v16, 16, v0
	v_and_b32_e32 v17, 0xffff0000, v0
	v_lshlrev_b32_e32 v48, 16, v3
	v_and_b32_e32 v12, 0xffff0000, v3
	s_waitcnt vmcnt(6)
	v_and_b32_e32 v14, 0xffff0000, v7
	v_lshlrev_b32_e32 v15, 16, v7
	v_lshlrev_b32_e32 v32, 16, v1
	v_and_b32_e32 v33, 0xffff0000, v1
	v_lshlrev_b32_e32 v34, 16, v2
	v_and_b32_e32 v35, 0xffff0000, v2
	v_lshlrev_b32_e32 v2, 16, v6
	v_and_b32_e32 v3, 0xffff0000, v6
	v_pk_mul_f32 v[6:7], v[16:17], v[16:17]
	v_pk_mul_f32 v[40:41], v[32:33], v[32:33]
	v_add_f32_e32 v6, v6, v7
	v_add_f32_e32 v6, v40, v6
	v_pk_mul_f32 v[44:45], v[34:35], v[34:35]
	v_add_f32_e32 v6, v41, v6
	v_add_f32_e32 v6, v44, v6
	v_add_f32_e32 v6, v45, v6
	v_lshlrev_b32_e32 v18, 16, v4
	v_and_b32_e32 v19, 0xffff0000, v4
	v_fmac_f32_e32 v6, v48, v48
	v_pk_mul_f32 v[36:37], v[18:19], v[18:19]
	v_fmac_f32_e32 v6, v12, v12
	v_lshlrev_b32_e32 v4, 16, v5
	v_and_b32_e32 v5, 0xffff0000, v5
	v_add_f32_e32 v6, v36, v6
	v_pk_mul_f32 v[42:43], v[4:5], v[4:5]
	v_add_f32_e32 v6, v37, v6
	v_add_f32_e32 v6, v42, v6
	v_pk_mul_f32 v[46:47], v[2:3], v[2:3]
	v_add_f32_e32 v6, v43, v6
	v_add_f32_e32 v6, v46, v6
	v_pk_mul_f32 v[0:1], v[14:15], v[14:15]
	v_add_f32_e32 v6, v47, v6
	v_add_f32_e32 v1, v1, v6
	v_add_f32_e32 v0, v0, v1
	ds_bpermute_b32 v1, v39, v0
	v_cndmask_b32_e32 v6, v196, v199, vcc
	v_lshlrev_b32_e32 v40, 2, v6
	v_mov_b32_e32 v13, v14
	s_waitcnt lgkmcnt(0)
	v_add_f32_e32 v0, v0, v1
	ds_bpermute_b32 v1, v40, v0
	s_waitcnt lgkmcnt(0)
	v_add_f32_e32 v0, v0, v1
	v_fmamk_f32 v0, v0, 0x3c800000, v170
	v_mul_f32_e32 v1, 0x4b800000, v0
	v_cmp_gt_f32_e32 vcc, s94, v0
	s_nop 1
	v_cndmask_b32_e32 v0, v0, v1, vcc
	v_rsq_f32_e32 v6, v0
	v_lshl_add_u64 v[0:1], s[34:35], 0, v[100:101]
	v_mul_f32_e32 v7, 0x45800000, v6
	v_cndmask_b32_e32 v6, v6, v7, vcc
	v_mul_f32_e32 v6, v65, v6
	v_pk_mul_f32 v[16:17], v[6:7], v[16:17] op_sel_hi:[0,1]
	v_pk_mul_f32 v[32:33], v[6:7], v[32:33] op_sel_hi:[0,1]
	v_pk_mul_f32 v[34:35], v[6:7], v[34:35] op_sel_hi:[0,1]
	v_mul_f32_e32 v7, v6, v48
	v_mul_f32_e32 v41, v6, v15
	v_pk_mul_f32 v[36:37], v[6:7], v[18:19] op_sel_hi:[0,1]
	v_pk_mul_f32 v[4:5], v[6:7], v[4:5] op_sel_hi:[0,1]
	v_pk_mul_f32 v[2:3], v[6:7], v[2:3] op_sel_hi:[0,1]
	v_pk_mul_f32 v[12:13], v[6:7], v[12:13] op_sel_hi:[0,1]
	s_waitcnt vmcnt(2)
	v_mul_f32_e32 v6, v30, v41
	v_mov_b32_e32 v30, v23
	v_pk_mul_f32 v[18:19], v[8:9], v[16:17]
	v_pk_mul_f32 v[16:17], v[10:11], v[32:33]
	v_pk_mul_f32 v[14:15], v[20:21], v[34:35]
	v_mul_f32_e32 v10, v22, v7
	v_pk_mul_f32 v[8:9], v[24:25], v[36:37]
	v_pk_mul_f32 v[4:5], v[26:27], v[4:5]
	v_pk_mul_f32 v[2:3], v[28:29], v[2:3]
	v_pk_mul_f32 v[12:13], v[30:31], v[12:13]
	s_and_saveexec_b64 s[0:1], s[38:39]
	s_cbranch_execz .LBB0_207
; __device__ __forceinline__ void unpack8(const u32x4 w, float* x) { x[0] = bflo(w.x); x[1] = bfhi(w.x); x[2] = bflo(w.y); x[3] = bfhi(w.y); x[4] = bflo(w.z); x[5] = bfhi(w.z); x[6] = bflo(w.w); x[7] = bfhi(w.w); }
; __device__ __forceinline__ u32x4 pack8(const float* x) { u32x4 w; w.x = pk2(x[0], x[1]); w.y = pk2(x[2], x[3]); w.z = pk2(x[4], x[5]); w.w = pk2(x[6], x[7]); return w; }
; __device__ __forceinline__ void phase_post1(const Params& p, int layer, const int wave_s) {
;     ...
;       if ((lane & 3) == 0) {
; #pragma unroll
;         for (int j = 0; j < 8; ++j) { float c, s; rope_cs(posf, p.inv_a[j], c, s); const float x1 = x[j], x2 = x[8 + j]; x[j] = x1 * c - x2 * s; x[8 + j] = x1 * s + x2 * c; }
;       }
;       ptr[0] = pack8(x); ptr[1] = pack8(x + 8); }
; #pragma unroll
;     for (int pass = 0; pass < 2; ++pass) {
;       const bool act = (pass == 0) || (lane < 32);
;       u32x4* ptr = (u32x4*)(pr + (pass == 0 ? C_BQ : C_BK) + lane * 8);
;       float x[8]; u32x4 w = {0u, 0u, 0u, 0u}; if (act) w = *ptr; unpack8(w, x);
	v_readlane_b32 s48, v254, 19
	s_mov_b32 s2, 0x6dc9c883
	s_mov_b32 s3, 0x3fc45f30
	v_mul_f32_e32 v7, s48, v38
	v_cvt_f64_f32_e32 v[20:21], v7
	v_mul_f64 v[22:23], v[20:21], s[2:3]
	v_rndne_f64_e32 v[22:23], v[22:23]
	v_fma_f64 v[20:21], v[20:21], s[2:3], -v[22:23]
	v_readlane_b32 s49, v254, 20
	v_cvt_f32_f64_e32 v7, v[20:21]
	v_sin_f32_e32 v20, v7
	v_cos_f32_e32 v22, v7
	v_mul_f32_e32 v7, s49, v38
	v_cvt_f64_f32_e32 v[24:25], v7
	v_mul_f64 v[26:27], v[24:25], s[2:3]
	v_rndne_f64_e32 v[26:27], v[26:27]
	v_fma_f64 v[24:25], v[24:25], s[2:3], -v[26:27]
	v_cvt_f32_f64_e32 v7, v[24:25]
	v_sin_f32_e32 v21, v7
	v_cos_f32_e32 v23, v7
	v_readlane_b32 s50, v254, 21
	v_readlane_b32 s51, v254, 22
	v_pk_mul_f32 v[24:25], v[8:9], v[20:21]
	v_pk_mul_f32 v[8:9], v[8:9], v[22:23]
	v_mul_f32_e32 v7, s50, v38
	v_pk_fma_f32 v[24:25], v[18:19], v[22:23], v[24:25] neg_lo:[0,0,1] neg_hi:[0,0,1]
	v_pk_fma_f32 v[8:9], v[18:19], v[20:21], v[8:9]
	v_cvt_f64_f32_e32 v[18:19], v7
	v_mul_f64 v[20:21], v[18:19], s[2:3]
	v_rndne_f64_e32 v[20:21], v[20:21]
	v_fma_f64 v[18:19], v[18:19], s[2:3], -v[20:21]
	v_cvt_f32_f64_e32 v7, v[18:19]
	v_sin_f32_e32 v18, v7
	v_cos_f32_e32 v20, v7
	v_mul_f32_e32 v7, s51, v38
	v_cvt_f64_f32_e32 v[22:23], v7
	v_mul_f64 v[26:27], v[22:23], s[2:3]
	v_rndne_f64_e32 v[26:27], v[26:27]
	v_fma_f64 v[22:23], v[22:23], s[2:3], -v[26:27]
	v_cvt_f32_f64_e32 v7, v[22:23]
	v_sin_f32_e32 v19, v7
	v_cos_f32_e32 v21, v7
	v_readlane_b32 s52, v254, 23
	v_readlane_b32 s53, v254, 24
	v_pk_mul_f32 v[22:23], v[4:5], v[18:19]
	v_pk_mul_f32 v[4:5], v[4:5], v[20:21]
	v_mul_f32_e32 v7, s52, v38
	v_pk_fma_f32 v[22:23], v[16:17], v[20:21], v[22:23] neg_lo:[0,0,1] neg_hi:[0,0,1]
	v_pk_fma_f32 v[4:5], v[16:17], v[18:19], v[4:5]
	v_cvt_f64_f32_e32 v[16:17], v7
	v_mul_f64 v[18:19], v[16:17], s[2:3]
	v_rndne_f64_e32 v[18:19], v[18:19]
	v_fma_f64 v[16:17], v[16:17], s[2:3], -v[18:19]
	v_cvt_f32_f64_e32 v7, v[16:17]
	v_sin_f32_e32 v16, v7
	v_cos_f32_e32 v18, v7
	v_mul_f32_e32 v7, s53, v38
	v_cvt_f64_f32_e32 v[20:21], v7
	v_mul_f64 v[26:27], v[20:21], s[2:3]
	v_rndne_f64_e32 v[26:27], v[26:27]
	v_fma_f64 v[20:21], v[20:21], s[2:3], -v[26:27]
	v_cvt_f32_f64_e32 v7, v[20:21]
	v_sin_f32_e32 v17, v7
	v_cos_f32_e32 v19, v7
	v_readlane_b32 s54, v254, 25
	v_readlane_b32 s55, v254, 26
	v_pk_mul_f32 v[20:21], v[2:3], v[16:17]
	v_pk_mul_f32 v[2:3], v[2:3], v[18:19]
	v_mul_f32_e32 v7, s54, v38
	v_pk_fma_f32 v[20:21], v[14:15], v[18:19], v[20:21] neg_lo:[0,0,1] neg_hi:[0,0,1]
	v_pk_fma_f32 v[2:3], v[14:15], v[16:17], v[2:3]
	v_cvt_f64_f32_e32 v[14:15], v7
	v_mul_f64 v[16:17], v[14:15], s[2:3]
	v_rndne_f64_e32 v[16:17], v[16:17]
	v_fma_f64 v[14:15], v[14:15], s[2:3], -v[16:17]
	v_cvt_f32_f64_e32 v7, v[14:15]
	v_sin_f32_e32 v14, v7
	v_cos_f32_e32 v16, v7
	v_mul_f32_e32 v7, s55, v38
	v_cvt_f64_f32_e32 v[28:29], v7
	v_mul_f64 v[30:31], v[28:29], s[2:3]
	v_rndne_f64_e32 v[30:31], v[30:31]
	v_fma_f64 v[28:29], v[28:29], s[2:3], -v[30:31]
	v_cvt_f32_f64_e32 v7, v[28:29]
	v_sin_f32_e32 v15, v7
	v_cos_f32_e32 v17, v7
	v_mov_b32_e32 v7, v13
	v_mul_f32_e32 v26, v6, v16
	v_mov_b32_e32 v11, v12
	v_pk_mul_f32 v[6:7], v[6:7], v[14:15]
	v_mul_f32_e32 v18, v10, v14
	v_pk_fma_f32 v[10:11], v[10:11], v[16:17], v[6:7] neg_lo:[0,0,1] neg_hi:[0,0,1]
	v_mov_b32_e32 v16, v15
	v_pk_mul_f32 v[6:7], v[12:13], v[16:17]
	v_mov_b32_e32 v16, v22
	v_mov_b32_e32 v19, v6
	v_mov_b32_e32 v27, v7
	v_pk_add_f32 v[6:7], v[18:19], v[26:27]
	v_mov_b32_e32 v18, v24
	v_mov_b32_e32 v19, v25
	v_mov_b32_e32 v17, v23
	v_mov_b32_e32 v14, v20
	v_mov_b32_e32 v15, v21
	v_mov_b32_e32 v12, v11
	v_mov_b32_e32 v13, v7
.LBB0_207:
	s_or_b64 exec, exec, s[0:1]
	s_add_i32 s0, s4, -16
	s_ashr_i32 s1, s0, 6
	s_and_b32 s0, s0, 63
	s_cmp_lt_i32 s4, 16
	v_cvt_f32_ubyte0_e32 v11, s0
	s_cselect_b64 vcc, -1, 0
	v_cndmask_b32_e32 v22, v11, v38, vcc
	v_bfe_u32 v11, v18, 16, 1
	v_add3_u32 v11, v18, v11, s15
	v_bfe_u32 v18, v19, 16, 1
	v_lshrrev_b32_e32 v11, 16, v11
	v_add3_u32 v18, v19, v18, s15
	v_and_or_b32 v18, v18, s14, v11
	v_bfe_u32 v11, v16, 16, 1
	v_add3_u32 v11, v16, v11, s15
	v_bfe_u32 v16, v17, 16, 1
	v_lshrrev_b32_e32 v11, 16, v11
	v_add3_u32 v16, v17, v16, s15
	v_and_or_b32 v19, v16, s14, v11
	v_bfe_u32 v11, v14, 16, 1
	v_add3_u32 v11, v14, v11, s15
	v_bfe_u32 v14, v15, 16, 1
	v_lshrrev_b32_e32 v11, 16, v11
	v_add3_u32 v14, v15, v14, s15
	v_and_or_b32 v20, v14, s14, v11
	v_bfe_u32 v11, v10, 16, 1
	v_add3_u32 v10, v10, v11, s15
	v_bfe_u32 v11, v12, 16, 1
	v_lshrrev_b32_e32 v10, 16, v10
	v_add3_u32 v11, v12, v11, s15
	v_and_or_b32 v21, v11, s14, v10
	v_bfe_u32 v10, v8, 16, 1
	v_add3_u32 v8, v8, v10, s15
	v_bfe_u32 v10, v9, 16, 1
	v_lshrrev_b32_e32 v8, 16, v8
	v_add3_u32 v9, v9, v10, s15
	v_and_or_b32 v8, v9, s14, v8
	v_bfe_u32 v9, v4, 16, 1
	v_add3_u32 v4, v4, v9, s15
	v_bfe_u32 v9, v5, 16, 1
	v_lshrrev_b32_e32 v4, 16, v4
	v_add3_u32 v5, v5, v9, s15
	v_and_or_b32 v9, v5, s14, v4
	v_bfe_u32 v4, v2, 16, 1
	v_add3_u32 v2, v2, v4, s15
	v_bfe_u32 v4, v3, 16, 1
	v_cvt_f32_i32_e32 v7, s1
	v_lshrrev_b32_e32 v2, 16, v2
	v_add3_u32 v3, v3, v4, s15
	v_and_or_b32 v10, v3, s14, v2
	v_bfe_u32 v2, v6, 16, 1
	v_add3_u32 v2, v6, v2, s15
	v_bfe_u32 v3, v13, 16, 1
	v_lshrrev_b32_e32 v2, 16, v2
	v_add3_u32 v3, v13, v3, s15
	v_cndmask_b32_e64 v7, v7, -1.0, vcc
	v_and_or_b32 v11, v3, s14, v2
	v_lshlrev_b32_e32 v168, 1, v68
	v_cmp_lt_i32_e32 vcc, v200, v197
	global_store_dwordx4 v[0:1], v[18:21], off
	global_store_dwordx4 v[0:1], v[8:11], off offset:16
	v_lshl_add_u64 v[12:13], s[34:35], 0, v[168:169]
	v_cndmask_b32_e32 v0, v196, v200, vcc
	v_cmp_lt_i32_e32 vcc, v201, v197
	s_movk_i32 s0, 0x1000
	v_lshlrev_b32_e32 v42, 2, v0
	v_cndmask_b32_e32 v0, v196, v201, vcc
	v_add_co_u32_e32 v14, vcc, s0, v12
	v_lshlrev_b32_e32 v41, 2, v0
	s_nop 0
	v_addc_co_u32_e32 v15, vcc, 0, v13, vcc
	v_cndmask_b32_e64 v43, v22, v7, s[40:41]
	s_waitcnt vmcnt(3)
	v_mov_b32_e32 v0, v134
	v_mov_b32_e32 v1, v135
	v_mov_b32_e32 v2, v136
	v_mov_b32_e32 v3, v137
	v_mov_b32_e32 v4, v114
	v_mov_b32_e32 v5, v115
	v_mov_b32_e32 v6, v116
	v_mov_b32_e32 v7, v117
	v_mov_b32_e32 v8, v118
	v_mov_b32_e32 v9, v119
	v_mov_b32_e32 v10, v120
	v_mov_b32_e32 v11, v121
	s_mov_b32 s0, 0x6dc9c883
	s_mov_b32 s1, 0x3fc45f30

; __device__ __forceinline__ void unpack8(const u32x4 w, float* x) { x[0] = bflo(w.x); x[1] = bfhi(w.x); x[2] = bflo(w.y); x[3] = bfhi(w.y); x[4] = bflo(w.z); x[5] = bfhi(w.z); x[6] = bflo(w.w); x[7] = bfhi(w.w); }
; __device__ __forceinline__ void phase_post1(const Params& p, int layer, const int wave_s) {
;     ...
;       float x[8]; u32x4 w = {0u, 0u, 0u, 0u}; if (act) w = *ptr; unpack8(w, x);
	v_lshlrev_b32_e32 v33, 16, v1

; __device__ __forceinline__ void rope_cs(float pos, float inv, float& c, float& s) {
;     ...
;   double rev = (double)ang * 0.15915494309189535; rev -= rint(rev);
; __device__ __forceinline__ void phase_post1(const Params& p, int layer, const int wave_s) {
;     ...
;         float c, s; rope_cs(posv, p.inv_b[(a & 3) * 8 + i], c, s);
	v_mul_f32_e32 v4, v43, v4

; __device__ __forceinline__ void rope_cs(float pos, float inv, float& c, float& s) {
;   const float ang = pos * inv;
;   double rev = (double)ang * 0.15915494309189535; rev -= rint(rev);
;   const float fr = (float)rev;
;   s = __builtin_amdgcn_sinf(fr); c = __builtin_amdgcn_cosf(fr);
; }
; __device__ __forceinline__ void phase_post1(const Params& p, int layer, const int wave_s) {
;     ...
;       const float posv = (a < 8) ? rowp : colp;
; #pragma unroll
;       for (int i = 0; i < 8; ++i) { const float y = x[i] * rs * wn[i]; const float other = __shfl_xor(y, 4);
;         float c, s; rope_cs(posv, p.inv_b[(a & 3) * 8 + i], c, s);
	v_mul_f32_e32 v8, v43, v8
	v_cvt_f64_f32_e32 v[16:17], v8
	v_mul_f64 v[18:19], v[16:17], s[0:1]
	v_rndne_f64_e32 v[18:19], v[18:19]
	v_fma_f64 v[16:17], v[16:17], s[0:1], -v[18:19]
	v_cvt_f32_f64_e32 v8, v[16:17]
	v_cos_f32_e32 v16, v8
	v_sin_f32_e32 v18, v8
	v_mul_f32_e32 v8, v43, v9
	v_cvt_f64_f32_e32 v[8:9], v8
	v_mul_f64 v[20:21], v[8:9], s[0:1]
	v_rndne_f64_e32 v[20:21], v[20:21]
	v_fma_f64 v[8:9], v[8:9], s[0:1], -v[20:21]
	v_cvt_f32_f64_e32 v8, v[8:9]
	v_cos_f32_e32 v20, v8
	v_sin_f32_e32 v22, v8
	v_mul_f32_e32 v8, v43, v10
	v_cvt_f64_f32_e32 v[8:9], v8
	v_mul_f64 v[24:25], v[8:9], s[0:1]
	v_rndne_f64_e32 v[24:25], v[24:25]
	v_fma_f64 v[8:9], v[8:9], s[0:1], -v[24:25]
	v_cvt_f32_f64_e32 v8, v[8:9]
	v_cos_f32_e32 v17, v8
	v_sin_f32_e32 v19, v8
	v_mul_f32_e32 v8, v43, v11
	v_cvt_f64_f32_e32 v[8:9], v8
	v_mul_f64 v[10:11], v[8:9], s[0:1]
	v_rndne_f64_e32 v[10:11], v[10:11]
	v_fma_f64 v[8:9], v[8:9], s[0:1], -v[10:11]
	v_cvt_f32_f64_e32 v8, v[8:9]
	v_cos_f32_e32 v21, v8
	v_sin_f32_e32 v23, v8
	v_cvt_f64_f32_e32 v[8:9], v4
	v_mul_f64 v[10:11], v[8:9], s[0:1]
	v_rndne_f64_e32 v[10:11], v[10:11]
	v_fma_f64 v[8:9], v[8:9], s[0:1], -v[10:11]
	v_cvt_f32_f64_e32 v4, v[8:9]
	v_cos_f32_e32 v26, v4
	v_sin_f32_e32 v30, v4
	v_mul_f32_e32 v4, v43, v5
	v_cvt_f64_f32_e32 v[4:5], v4
	v_mul_f64 v[8:9], v[4:5], s[0:1]
	v_rndne_f64_e32 v[8:9], v[8:9]
	v_fma_f64 v[4:5], v[4:5], s[0:1], -v[8:9]
	v_cvt_f32_f64_e32 v4, v[4:5]
	v_cos_f32_e32 v24, v4
	v_sin_f32_e32 v28, v4
	v_mul_f32_e32 v4, v43, v6
	v_cvt_f64_f32_e32 v[4:5], v4
	v_mul_f64 v[8:9], v[4:5], s[0:1]
	v_rndne_f64_e32 v[8:9], v[8:9]
	v_fma_f64 v[4:5], v[4:5], s[0:1], -v[8:9]
	v_cvt_f32_f64_e32 v4, v[4:5]
	v_cos_f32_e32 v27, v4
	v_sin_f32_e32 v31, v4
	v_mul_f32_e32 v4, v43, v7
	v_cvt_f64_f32_e32 v[4:5], v4
	v_mul_f64 v[6:7], v[4:5], s[0:1]
	v_rndne_f64_e32 v[6:7], v[6:7]
	v_fma_f64 v[4:5], v[4:5], s[0:1], -v[6:7]
	v_cvt_f32_f64_e32 v4, v[4:5]
	v_and_b32_e32 v1, 0xffff0000, v1
	v_cos_f32_e32 v25, v4
	v_sin_f32_e32 v29, v4
	v_mov_b32_e32 v4, v1
	v_mov_b32_e32 v5, v33
	v_pk_mul_f32 v[34:35], v[4:5], v[4:5]
	v_mov_b32_e32 v4, v122
	v_mov_b32_e32 v5, v123
	v_mov_b32_e32 v6, v124
	v_mov_b32_e32 v7, v125
	v_mov_b32_e32 v8, v126
	v_mov_b32_e32 v9, v127
	v_mov_b32_e32 v10, v128
	v_mov_b32_e32 v11, v129
	v_lshlrev_b32_e32 v32, 16, v0
	v_and_b32_e32 v0, 0xffff0000, v0
	s_mov_b64 s[0:1], 0x1400

; __device__ __forceinline__ void phase_post1(const Params& p, int layer, const int wave_s) {
;     ...
;       for (int i = 0; i < 8; ++i) ss += x[i] * x[i];
	v_mov_b32_e32 v48, v4
	v_mul_f32_e32 v4, v32, v32

; __device__ __forceinline__ float sum16(float v) { v += __shfl_xor(v, 1); v += __shfl_xor(v, 2); v += __shfl_xor(v, 4); v += __shfl_xor(v, 8); return v; }
; __device__ __forceinline__ u32x4 pack8(const float* x) { u32x4 w; w.x = pk2(x[0], x[1]); w.y = pk2(x[2], x[3]); w.z = pk2(x[4], x[5]); w.w = pk2(x[6], x[7]); return w; }
; __device__ __forceinline__ void phase_post1(const Params& p, int layer, const int wave_s) {
;     ...
;       for (int i = 0; i < 8; ++i) ss += x[i] * x[i];
;       ss = sum16(ss);
;       const float rs = rsqrtf(ss * (1.f / 128.f) + EPS) * (pass == 0 ? QS_B : 1.f);
;       const int a = lane & 15; const float* wn = (pass == 0 ? bqn : bkn) + a * 8;
;       const float posv = (a < 8) ? rowp : colp;
; #pragma unroll
;       for (int i = 0; i < 8; ++i) { const float y = x[i] * rs * wn[i]; const float other = __shfl_xor(y, 4);
;         float c, s; rope_cs(posv, p.inv_b[(a & 3) * 8 + i], c, s);
;         x[i] = (a & 4) ? other * s + y * c : y * c - other * s; }
;       if (act) *ptr = pack8(x);
	v_mov_b32_e32 v36, v8
	v_lshlrev_b32_e32 v8, 16, v2
	v_and_b32_e32 v2, 0xffff0000, v2
	v_fmac_f32_e32 v4, v0, v0
	v_mov_b32_e32 v44, v2
	v_mov_b32_e32 v45, v8
	v_add_f32_e32 v4, v35, v4
	v_mov_b32_e32 v37, v10
	v_mov_b32_e32 v10, v9
	v_lshlrev_b32_e32 v9, 16, v3
	v_and_b32_e32 v3, 0xffff0000, v3
	v_pk_mul_f32 v[44:45], v[44:45], v[44:45]
	v_add_f32_e32 v4, v34, v4
	v_mov_b32_e32 v46, v3
	v_mov_b32_e32 v47, v9
	v_add_f32_e32 v4, v45, v4
	v_pk_mul_f32 v[46:47], v[46:47], v[46:47]
	v_add_f32_e32 v4, v44, v4
	v_add_f32_e32 v4, v47, v4
	v_add_f32_e32 v4, v46, v4
	v_mov_b32_e32 v49, v6
	v_mov_b32_e32 v6, v5
	ds_bpermute_b32 v5, v39, v4
	s_waitcnt lgkmcnt(0)
	v_add_f32_e32 v4, v4, v5
	ds_bpermute_b32 v5, v40, v4
	s_waitcnt lgkmcnt(0)
	v_add_f32_e32 v4, v4, v5
	ds_bpermute_b32 v5, v42, v4
	s_waitcnt lgkmcnt(0)
	v_add_f32_e32 v4, v4, v5
	ds_bpermute_b32 v5, v41, v4
	s_waitcnt lgkmcnt(0)
	v_add_f32_e32 v4, v4, v5
	v_fmamk_f32 v4, v4, 0x3c000000, v170
	v_cmp_gt_f32_e32 vcc, s94, v4
	v_mul_f32_e32 v5, 0x4b800000, v4
	s_nop 0
	v_cndmask_b32_e32 v4, v4, v5, vcc
	v_rsq_f32_e32 v4, v4
	s_nop 0
	v_mul_f32_e32 v5, 0x45800000, v4
	v_cndmask_b32_e32 v4, v4, v5, vcc
	v_mul_f32_e32 v4, 0x3e0293ee, v4
	v_pk_mul_f32 v[0:1], v[4:5], v[0:1] op_sel_hi:[0,1]
	v_pk_mul_f32 v[0:1], v[10:11], v[0:1]
	v_pk_mul_f32 v[2:3], v[4:5], v[2:3] op_sel_hi:[0,1]
	v_pk_mul_f32 v[32:33], v[4:5], v[32:33] op_sel_hi:[0,1]
	ds_bpermute_b32 v10, v42, v0
	ds_bpermute_b32 v11, v42, v1
	v_pk_mul_f32 v[8:9], v[4:5], v[8:9] op_sel_hi:[0,1]
	v_pk_mul_f32 v[2:3], v[6:7], v[2:3]
	v_pk_mul_f32 v[32:33], v[36:37], v[32:33]
	v_pk_mul_f32 v[8:9], v[48:49], v[8:9]
	ds_bpermute_b32 v4, v42, v2
	ds_bpermute_b32 v5, v42, v3
	ds_bpermute_b32 v34, v42, v32
	ds_bpermute_b32 v35, v42, v33
	ds_bpermute_b32 v36, v42, v8
	ds_bpermute_b32 v37, v42, v9
	s_waitcnt lgkmcnt(6)
	v_pk_mul_f32 v[10:11], v[22:23], v[10:11]
	s_waitcnt lgkmcnt(4)
	v_pk_mul_f32 v[4:5], v[28:29], v[4:5]
	v_cndmask_b32_e64 v11, v11, -v11, s[42:43]
	v_cndmask_b32_e64 v10, v10, -v10, s[42:43]
	s_waitcnt lgkmcnt(2)
	v_pk_mul_f32 v[6:7], v[18:19], v[34:35]
	v_pk_fma_f32 v[0:1], v[0:1], v[20:21], v[10:11]
	s_waitcnt lgkmcnt(0)
	v_pk_mul_f32 v[10:11], v[30:31], v[36:37]
	v_cndmask_b32_e64 v5, v5, -v5, s[42:43]
	v_cndmask_b32_e64 v4, v4, -v4, s[42:43]
	v_cndmask_b32_e64 v7, v7, -v7, s[42:43]
	v_cndmask_b32_e64 v6, v6, -v6, s[42:43]
	v_cndmask_b32_e64 v11, v11, -v11, s[42:43]
	v_cndmask_b32_e64 v10, v10, -v10, s[42:43]
	v_pk_fma_f32 v[2:3], v[2:3], v[24:25], v[4:5]
	v_pk_fma_f32 v[6:7], v[32:33], v[16:17], v[6:7]
	v_pk_fma_f32 v[8:9], v[8:9], v[26:27], v[10:11]
	v_bfe_u32 v4, v3, 16, 1
	v_bfe_u32 v5, v2, 16, 1
	v_bfe_u32 v10, v1, 16, 1
	v_bfe_u32 v11, v0, 16, 1
	v_add3_u32 v0, v0, v11, s15
	v_add3_u32 v1, v1, v10, s15
	v_add3_u32 v2, v2, v5, s15
	v_add3_u32 v3, v3, v4, s15
	v_bfe_u32 v4, v6, 16, 1
	v_bfe_u32 v5, v7, 16, 1
	v_bfe_u32 v10, v8, 16, 1
	v_bfe_u32 v11, v9, 16, 1
	v_add3_u32 v9, v9, v11, s15
	v_add3_u32 v8, v8, v10, s15
	v_add3_u32 v5, v7, v5, s15
	v_add3_u32 v4, v6, v4, s15
	v_lshrrev_b32_e32 v4, 16, v4
	v_lshrrev_b32_e32 v5, 16, v5
	v_lshrrev_b32_e32 v6, 16, v8
	v_lshrrev_b32_e32 v7, 16, v9
	v_and_or_b32 v3, v3, s14, v7
	v_and_or_b32 v2, v2, s14, v6
	v_and_or_b32 v1, v1, s14, v5
	v_and_or_b32 v0, v0, s14, v4
	global_store_dwordx4 v[14:15], v[0:3], off
	v_lshl_add_u64 v[4:5], v[12:13], 0, s[0:1]
	s_nop 0
	v_mov_b32_e32 v0, 0
	v_mov_b32_e32 v1, 0
	v_mov_b32_e32 v2, 0
	v_mov_b32_e32 v3, 0
	s_waitcnt vmcnt(3)
	s_and_saveexec_b64 s[0:1], s[36:37]
	s_cbranch_execz .LBB0_209
	v_mov_b32_e32 v0, v138
	v_mov_b32_e32 v1, v139
	v_mov_b32_e32 v2, v140
	v_mov_b32_e32 v3, v141
.LBB0_209:
	s_or_b64 exec, exec, s[0:1]
	v_mov_b32_e32 v6, v142
	v_mov_b32_e32 v7, v143
	v_mov_b32_e32 v8, v144
	v_mov_b32_e32 v9, v145
	v_mov_b32_e32 v10, v146
	v_mov_b32_e32 v11, v147
	v_mov_b32_e32 v12, v148
	v_mov_b32_e32 v13, v149

; __device__ __forceinline__ float sum16(float v) { v += __shfl_xor(v, 1); v += __shfl_xor(v, 2); v += __shfl_xor(v, 4); v += __shfl_xor(v, 8); return v; }
; __device__ __forceinline__ void phase_post1(const Params& p, int layer, const int wave_s) {
;     ...
;       float ss = 0.f;
; #pragma unroll
;       for (int i = 0; i < 8; ++i) ss += x[i] * x[i];
;       ss = sum16(ss);
;       const float rs = rsqrtf(ss * (1.f / 128.f) + EPS) * (pass == 0 ? QS_B : 1.f);
	v_lshlrev_b32_e32 v15, 16, v1
	v_lshlrev_b32_e32 v14, 16, v0
	v_and_b32_e32 v1, 0xffff0000, v1
	v_and_b32_e32 v0, 0xffff0000, v0
	v_mov_b32_e32 v18, v1
	v_mov_b32_e32 v19, v15
	v_mul_f32_e32 v24, v14, v14
	v_lshlrev_b32_e32 v16, 16, v2
	v_and_b32_e32 v2, 0xffff0000, v2
	v_pk_mul_f32 v[18:19], v[18:19], v[18:19]
	v_fmac_f32_e32 v24, v0, v0
	v_mov_b32_e32 v20, v2
	v_mov_b32_e32 v21, v16
	v_add_f32_e32 v19, v19, v24
	v_lshlrev_b32_e32 v17, 16, v3
	v_and_b32_e32 v3, 0xffff0000, v3
	v_pk_mul_f32 v[20:21], v[20:21], v[20:21]
	v_add_f32_e32 v18, v18, v19
	v_mov_b32_e32 v22, v3
	v_mov_b32_e32 v23, v17
	v_add_f32_e32 v18, v21, v18
	v_pk_mul_f32 v[22:23], v[22:23], v[22:23]
	v_add_f32_e32 v18, v20, v18
	v_add_f32_e32 v18, v23, v18
	v_add_f32_e32 v18, v22, v18
	ds_bpermute_b32 v19, v39, v18
	s_bfe_i64 s[28:29], s[4:5], 0x200000
	s_waitcnt lgkmcnt(0)
	v_add_f32_e32 v18, v18, v19
	ds_bpermute_b32 v19, v40, v18
	s_waitcnt lgkmcnt(0)
	v_add_f32_e32 v18, v18, v19
	ds_bpermute_b32 v19, v42, v18
	s_waitcnt lgkmcnt(0)
	v_add_f32_e32 v18, v18, v19
	ds_bpermute_b32 v19, v41, v18
	s_waitcnt lgkmcnt(0)
	v_add_f32_e32 v18, v18, v19
	v_fmamk_f32 v18, v18, 0x3c000000, v170
	v_mul_f32_e32 v19, 0x4b800000, v18
	v_cmp_gt_f32_e32 vcc, s94, v18
	s_nop 1
	v_cndmask_b32_e32 v18, v18, v19, vcc
	v_rsq_f32_e32 v18, v18
	s_nop 0
	v_mul_f32_e32 v19, 0x45800000, v18
	v_cndmask_b32_e32 v18, v18, v19, vcc
	v_pk_mul_f32 v[14:15], v[18:19], v[14:15] op_sel_hi:[0,1]
	v_pk_mul_f32 v[0:1], v[18:19], v[0:1] op_sel_hi:[0,1]
	v_pk_mul_f32 v[16:17], v[18:19], v[16:17] op_sel_hi:[0,1]
	v_pk_mul_f32 v[2:3], v[18:19], v[2:3] op_sel_hi:[0,1]

; __device__ __forceinline__ void phase_post1(const Params& p, int layer, const int wave_s) {
;     ...
;       for (int i = 0; i < 8; ++i) { const float y = x[i] * rs * wn[i]; const float other = __shfl_xor(y, 4);
	v_mov_b32_e32 v18, v6
	v_mov_b32_e32 v19, v8
	v_mov_b32_e32 v8, v7

; __device__ __forceinline__ void phase_post1(const Params& p, int layer, const int wave_s) {
;     ...
;       for (int i = 0; i < 8; ++i) { const float y = x[i] * rs * wn[i]; const float other = __shfl_xor(y, 4);
;         float c, s; rope_cs(posv, p.inv_b[(a & 3) * 8 + i], c, s);
	v_mov_b32_e32 v6, v10
	v_mov_b32_e32 v7, v12
	v_mov_b32_e32 v12, v11
	v_pk_mul_f32 v[18:19], v[18:19], v[14:15]
	v_pk_mul_f32 v[14:15], v[8:9], v[0:1]
	v_pk_mul_f32 v[10:11], v[6:7], v[16:17]
	v_pk_mul_f32 v[6:7], v[12:13], v[2:3]
	ds_bpermute_b32 v20, v42, v18
	ds_bpermute_b32 v16, v42, v14
	ds_bpermute_b32 v21, v42, v19
	ds_bpermute_b32 v17, v42, v15
	ds_bpermute_b32 v12, v42, v10
	ds_bpermute_b32 v8, v42, v6
	ds_bpermute_b32 v13, v42, v11
	ds_bpermute_b32 v9, v42, v7
	s_and_saveexec_b64 s[0:1], s[36:37]
	s_cbranch_execz .LBB0_211
	v_mov_b32_e32 v0, v114
	v_mov_b32_e32 v1, v115
	v_mov_b32_e32 v2, v116
	v_mov_b32_e32 v3, v117
	v_mov_b32_e32 v28, v118
	v_mov_b32_e32 v29, v119
	v_mov_b32_e32 v30, v120
	v_mov_b32_e32 v31, v121
	s_mov_b32 s2, 0x6dc9c883
	s_mov_b32 s3, 0x3fc45f30

; __device__ __forceinline__ void phase_post1(const Params& p, int layer, const int wave_s) {
;     ...
;         float c, s; rope_cs(posv, p.inv_b[(a & 3) * 8 + i], c, s);
	v_mul_f32_e32 v0, v43, v0

; __device__ __forceinline__ u32x4 pack8(const float* x) { u32x4 w; w.x = pk2(x[0], x[1]); w.y = pk2(x[2], x[3]); w.z = pk2(x[4], x[5]); w.w = pk2(x[6], x[7]); return w; }
; __device__ __forceinline__ void rope_cs(float pos, float inv, float& c, float& s) {
;   const float ang = pos * inv;
;   double rev = (double)ang * 0.15915494309189535; rev -= rint(rev);
;   const float fr = (float)rev;
;   s = __builtin_amdgcn_sinf(fr); c = __builtin_amdgcn_cosf(fr);
; }
; __device__ __forceinline__ void phase_post1(const Params& p, int layer, const int wave_s) {
;     ...
;       const float posv = (a < 8) ? rowp : colp;
; #pragma unroll
;       for (int i = 0; i < 8; ++i) { const float y = x[i] * rs * wn[i]; const float other = __shfl_xor(y, 4);
;         float c, s; rope_cs(posv, p.inv_b[(a & 3) * 8 + i], c, s);
;         x[i] = (a & 4) ? other * s + y * c : y * c - other * s; }
;       if (act) *ptr = pack8(x);
	v_mul_f32_e32 v22, v43, v28
	v_cvt_f64_f32_e32 v[22:23], v22
	v_mul_f64 v[24:25], v[22:23], s[2:3]
	v_rndne_f64_e32 v[24:25], v[24:25]
	v_fma_f64 v[22:23], v[22:23], s[2:3], -v[24:25]
	v_cvt_f32_f64_e32 v23, v[22:23]
	v_cos_f32_e32 v22, v23
	v_sin_f32_e32 v24, v23
	v_mul_f32_e32 v23, v43, v29
	v_cvt_f64_f32_e32 v[26:27], v23
	v_mul_f64 v[28:29], v[26:27], s[2:3]
	v_rndne_f64_e32 v[28:29], v[28:29]
	v_fma_f64 v[26:27], v[26:27], s[2:3], -v[28:29]
	v_cvt_f32_f64_e32 v23, v[26:27]
	v_cos_f32_e32 v26, v23
	v_sin_f32_e32 v28, v23
	v_mul_f32_e32 v23, v43, v30
	v_cvt_f64_f32_e32 v[32:33], v23
	v_mul_f64 v[34:35], v[32:33], s[2:3]
	v_rndne_f64_e32 v[34:35], v[34:35]
	v_mul_f32_e32 v27, v43, v31
	v_fma_f64 v[32:33], v[32:33], s[2:3], -v[34:35]
	v_cvt_f64_f32_e32 v[30:31], v27
	v_cvt_f32_f64_e32 v25, v[32:33]
	v_mul_f64 v[32:33], v[30:31], s[2:3]
	v_rndne_f64_e32 v[32:33], v[32:33]
	v_fma_f64 v[30:31], v[30:31], s[2:3], -v[32:33]
	v_cvt_f32_f64_e32 v29, v[30:31]
	v_cvt_f64_f32_e32 v[30:31], v0
	v_mul_f64 v[32:33], v[30:31], s[2:3]
	v_rndne_f64_e32 v[32:33], v[32:33]
	v_fma_f64 v[30:31], v[30:31], s[2:3], -v[32:33]
	v_cvt_f32_f64_e32 v0, v[30:31]
	v_cos_f32_e32 v30, v0
	v_sin_f32_e32 v32, v0
	v_mul_f32_e32 v0, v43, v1
	v_cvt_f64_f32_e32 v[0:1], v0
	v_mul_f64 v[34:35], v[0:1], s[2:3]
	v_rndne_f64_e32 v[34:35], v[34:35]
	v_fma_f64 v[0:1], v[0:1], s[2:3], -v[34:35]
	v_cvt_f32_f64_e32 v1, v[0:1]
	v_cos_f32_e32 v0, v1
	v_sin_f32_e32 v34, v1
	v_mul_f32_e32 v1, v43, v2
	v_cvt_f64_f32_e32 v[36:37], v1
	v_mul_f64 v[44:45], v[36:37], s[2:3]
	v_rndne_f64_e32 v[44:45], v[44:45]
	v_fma_f64 v[36:37], v[36:37], s[2:3], -v[44:45]
	v_cvt_f32_f64_e32 v1, v[36:37]
	v_cos_f32_e32 v31, v1
	v_sin_f32_e32 v33, v1
	v_mul_f32_e32 v1, v43, v3
	v_cvt_f64_f32_e32 v[2:3], v1
	v_mul_f64 v[36:37], v[2:3], s[2:3]
	v_rndne_f64_e32 v[36:37], v[36:37]
	v_fma_f64 v[2:3], v[2:3], s[2:3], -v[36:37]
	v_cvt_f32_f64_e32 v2, v[2:3]
	v_sin_f32_e32 v35, v2
	v_cos_f32_e32 v23, v25
	v_sin_f32_e32 v25, v25
	v_cos_f32_e32 v27, v29
	v_sin_f32_e32 v29, v29
	v_cos_f32_e32 v1, v2
	s_waitcnt lgkmcnt(0)
	v_pk_mul_f32 v[8:9], v[34:35], v[8:9]
	v_pk_mul_f32 v[2:3], v[24:25], v[20:21]
	v_pk_mul_f32 v[12:13], v[32:33], v[12:13]
	v_cndmask_b32_e64 v9, v9, -v9, s[42:43]
	v_cndmask_b32_e64 v8, v8, -v8, s[42:43]
	v_cndmask_b32_e64 v3, v3, -v3, s[42:43]
	v_cndmask_b32_e64 v2, v2, -v2, s[42:43]
	v_pk_mul_f32 v[16:17], v[28:29], v[16:17]
	v_cndmask_b32_e64 v13, v13, -v13, s[42:43]
	v_cndmask_b32_e64 v12, v12, -v12, s[42:43]
	v_pk_fma_f32 v[0:1], v[6:7], v[0:1], v[8:9]
	v_pk_fma_f32 v[2:3], v[18:19], v[22:23], v[2:3]
	v_cndmask_b32_e64 v17, v17, -v17, s[42:43]
	v_cndmask_b32_e64 v16, v16, -v16, s[42:43]
	v_pk_fma_f32 v[10:11], v[10:11], v[30:31], v[12:13]
	v_bfe_u32 v6, v1, 16, 1
	v_bfe_u32 v7, v0, 16, 1
	v_pk_fma_f32 v[14:15], v[14:15], v[26:27], v[16:17]
	v_add3_u32 v0, v0, v7, s15
	v_add3_u32 v1, v1, v6, s15
	v_bfe_u32 v6, v2, 16, 1
	v_bfe_u32 v7, v3, 16, 1
	v_bfe_u32 v12, v10, 16, 1
	v_bfe_u32 v13, v11, 16, 1
	v_bfe_u32 v8, v15, 16, 1
	v_bfe_u32 v9, v14, 16, 1
	v_add3_u32 v11, v11, v13, s15
	v_add3_u32 v10, v10, v12, s15
	v_add3_u32 v3, v3, v7, s15
	v_add3_u32 v2, v2, v6, s15
	v_add3_u32 v9, v14, v9, s15
	v_add3_u32 v8, v15, v8, s15
	v_lshrrev_b32_e32 v6, 16, v2
	v_lshrrev_b32_e32 v7, 16, v3
	v_lshrrev_b32_e32 v2, 16, v10
	v_lshrrev_b32_e32 v3, 16, v11
	v_and_or_b32 v3, v1, s14, v3
	v_and_or_b32 v2, v0, s14, v2
	v_and_or_b32 v1, v8, s14, v7
	v_and_or_b32 v0, v9, s14, v6
	global_store_dwordx4 v[4:5], v[0:3], off
